# swiglu: per-unit row table (x, c*rstd) computed once per row in LDS by a pre-pass after the first K iteration; the per-thread rstd reduction code removed from the epilogue
# speedup vs baseline: 1.0026x; 1.0026x over previous
.Lswi_nobar:
.Lpeel_357:
	s_add_i32 s86, s42, 2
	s_add_u32 s29, s16, 0xfffc0080
	s_addc_u32 s37, s17, -1
	s_add_i32 s74, 0, 0x10000
	s_cmp_eq_u32 s20, s42
	s_cselect_b32 s73, s9, s37
	s_cselect_b32 s72, s13, s29
	v_add_u32_e32 v170, s74, v179
	s_cselect_b32 s43, s28, s57
	s_cselect_b32 s42, s39, s56
	s_add_i32 s29, 0, 0x14000
	ds_read_b128 v[130:133], v170
	ds_read_b128 v[180:183], v170 offset:1024
	ds_read_b128 v[184:187], v170 offset:2048
	ds_read_b128 v[188:191], v170 offset:3072
	v_add_u32_e32 v170, s29, v179
	ds_read_b128 v[192:195], v170
	ds_read_b128 v[196:199], v170 offset:1024
	ds_read_b128 v[204:207], v170 offset:2048
	ds_read_b128 v[208:211], v170 offset:3072
	s_add_i32 m0, s4, 0xc000
	ds_read_b128 v[212:215], v143
	ds_read_b128 v[216:219], v143 offset:1024
	ds_read_b128 v[220:223], v143 offset:2048
	ds_read_b128 v[224:227], v143 offset:3072
	ds_read_b128 v[228:231], v143 offset:4096
	ds_read_b128 v[232:235], v143 offset:5120
	ds_read_b128 v[236:239], v143 offset:6144
	ds_read_b128 v[240:243], v143 offset:7168
	global_load_lds_dwordx4 v174, s[16:17]
	s_add_i32 m0, s4, 0xe000
	s_nop 0
	global_load_lds_dwordx4 v176, s[16:17]
	s_waitcnt vmcnt(8)
	s_waitcnt lgkmcnt(0)
	s_setprio 1
	s_barrier
	v_mfma_f32_16x16x32_bf16 v[126:129], v[130:133], v[212:215], 0
	v_mfma_f32_16x16x32_bf16 v[118:121], v[184:187], v[212:215], 0
	v_mfma_f32_16x16x32_bf16 v[110:113], v[130:133], v[220:223], 0
	v_mfma_f32_16x16x32_bf16 v[102:105], v[184:187], v[220:223], 0
	v_mfma_f32_16x16x32_bf16 v[94:97], v[130:133], v[228:231], 0
	v_mfma_f32_16x16x32_bf16 v[86:89], v[184:187], v[228:231], 0
	v_mfma_f32_16x16x32_bf16 v[78:81], v[130:133], v[236:239], 0
	v_mfma_f32_16x16x32_bf16 v[70:73], v[184:187], v[236:239], 0
	v_mfma_f32_16x16x32_bf16 v[126:129], v[180:183], v[216:219], v[126:129]
	v_mfma_f32_16x16x32_bf16 v[118:121], v[188:191], v[216:219], v[118:121]
	v_mfma_f32_16x16x32_bf16 v[110:113], v[180:183], v[224:227], v[110:113]
	v_mfma_f32_16x16x32_bf16 v[102:105], v[188:191], v[224:227], v[102:105]
	v_mfma_f32_16x16x32_bf16 v[94:97], v[180:183], v[232:235], v[94:97]
	v_mfma_f32_16x16x32_bf16 v[86:89], v[188:191], v[232:235], v[86:89]
	v_mfma_f32_16x16x32_bf16 v[78:81], v[180:183], v[240:243], v[78:81]
	v_mfma_f32_16x16x32_bf16 v[70:73], v[188:191], v[240:243], v[70:73]
	v_mfma_f32_16x16x32_bf16 v[122:125], v[192:195], v[212:215], 0
	v_mfma_f32_16x16x32_bf16 v[114:117], v[204:207], v[212:215], 0
	v_mfma_f32_16x16x32_bf16 v[106:109], v[192:195], v[220:223], 0
	v_mfma_f32_16x16x32_bf16 v[98:101], v[204:207], v[220:223], 0
	v_mfma_f32_16x16x32_bf16 v[90:93], v[192:195], v[228:231], 0
	v_mfma_f32_16x16x32_bf16 v[82:85], v[204:207], v[228:231], 0
	v_mfma_f32_16x16x32_bf16 v[74:77], v[192:195], v[236:239], 0
	v_mfma_f32_16x16x32_bf16 v[66:69], v[204:207], v[236:239], 0
	v_mfma_f32_16x16x32_bf16 v[122:125], v[196:199], v[216:219], v[122:125]
	v_mfma_f32_16x16x32_bf16 v[114:117], v[208:211], v[216:219], v[114:117]
	v_mfma_f32_16x16x32_bf16 v[106:109], v[196:199], v[224:227], v[106:109]
	v_mfma_f32_16x16x32_bf16 v[98:101], v[208:211], v[224:227], v[98:101]
	v_mfma_f32_16x16x32_bf16 v[90:93], v[196:199], v[232:235], v[90:93]
	v_mfma_f32_16x16x32_bf16 v[82:85], v[208:211], v[232:235], v[82:85]
	v_mfma_f32_16x16x32_bf16 v[74:77], v[196:199], v[240:243], v[74:77]
	v_mfma_f32_16x16x32_bf16 v[66:69], v[208:211], v[240:243], v[66:69]
	s_barrier
	s_setprio 0
	s_add_i32 s37, s74, s84
	v_lshl_add_u64 v[244:245], s[42:43], 0, v[138:139]
	s_mov_b32 m0, s37
	ds_read_b128 v[212:215], v143 offset:16384
	ds_read_b128 v[216:219], v143 offset:17408
	ds_read_b128 v[220:223], v143 offset:18432
	ds_read_b128 v[224:227], v143 offset:19456
	ds_read_b128 v[228:231], v143 offset:20480
	ds_read_b128 v[232:235], v143 offset:21504
	ds_read_b128 v[236:239], v143 offset:22528
	ds_read_b128 v[240:243], v143 offset:23552
	global_load_lds_dwordx4 v[244:245], off
	s_add_i32 m0, s37, 0x2000
	s_add_u32 s74, s42, 0x40000
	v_lshl_add_u64 v[246:247], s[42:43], 0, v[134:135]
	s_addc_u32 s75, s43, 0
	s_add_i32 s29, s29, s84
	global_load_lds_dwordx4 v[246:247], off
	s_mov_b32 m0, s29
	v_lshl_add_u64 v[170:171], s[72:73], 0, v[136:137]
	global_load_lds_dwordx4 v138, s[74:75]
	s_add_i32 m0, s29, 0x2000
	s_nop 0
	global_load_lds_dwordx4 v134, s[74:75]
	v_lshl_add_u64 v[248:249], s[72:73], 0, v[140:141]
	s_mov_b32 m0, s4
	s_nop 0
	global_load_lds_dwordx4 v[248:249], off
	s_mov_b32 m0, s5
	s_nop 0
	global_load_lds_dwordx4 v[170:171], off
	s_lshl_b32 s101, s38, 14
	s_add_i32 s101, s101, s84
	s_add_u32 s100, s66, s101
	s_addc_u32 s101, s67, 0
	v_lshlrev_b32_e32 v172, 4, v163
	v_add_u32_e32 v173, 0x2000, v172
	s_add_i32 m0, s84, 0x20000
	s_nop 0
	global_load_lds_dwordx4 v172, s[100:101]
	s_add_i32 m0, s84, 0x22000
	s_nop 0
	global_load_lds_dwordx4 v173, s[100:101]
	s_waitcnt vmcnt(8)
	s_waitcnt lgkmcnt(0)
	s_setprio 1
	s_barrier
	v_mfma_f32_16x16x32_bf16 v[62:65], v[130:133], v[212:215], 0
	v_mfma_f32_16x16x32_bf16 v[54:57], v[184:187], v[212:215], 0
	v_mfma_f32_16x16x32_bf16 v[46:49], v[130:133], v[220:223], 0
	v_mfma_f32_16x16x32_bf16 v[38:41], v[184:187], v[220:223], 0
	v_mfma_f32_16x16x32_bf16 v[30:33], v[130:133], v[228:231], 0
	v_mfma_f32_16x16x32_bf16 v[22:25], v[184:187], v[228:231], 0
	v_mfma_f32_16x16x32_bf16 v[14:17], v[130:133], v[236:239], 0
	v_mfma_f32_16x16x32_bf16 v[6:9], v[184:187], v[236:239], 0
	v_mfma_f32_16x16x32_bf16 v[62:65], v[180:183], v[216:219], v[62:65]
	v_mfma_f32_16x16x32_bf16 v[54:57], v[188:191], v[216:219], v[54:57]
	v_mfma_f32_16x16x32_bf16 v[46:49], v[180:183], v[224:227], v[46:49]
	v_mfma_f32_16x16x32_bf16 v[38:41], v[188:191], v[224:227], v[38:41]
	v_mfma_f32_16x16x32_bf16 v[30:33], v[180:183], v[232:235], v[30:33]
	v_mfma_f32_16x16x32_bf16 v[22:25], v[188:191], v[232:235], v[22:25]
	v_mfma_f32_16x16x32_bf16 v[14:17], v[180:183], v[240:243], v[14:17]
	v_mfma_f32_16x16x32_bf16 v[6:9], v[188:191], v[240:243], v[6:9]
	v_mfma_f32_16x16x32_bf16 v[58:61], v[192:195], v[212:215], 0
	v_mfma_f32_16x16x32_bf16 v[50:53], v[204:207], v[212:215], 0
	v_mfma_f32_16x16x32_bf16 v[42:45], v[192:195], v[220:223], 0
	v_mfma_f32_16x16x32_bf16 v[34:37], v[204:207], v[220:223], 0
	v_mfma_f32_16x16x32_bf16 v[26:29], v[192:195], v[228:231], 0
	v_mfma_f32_16x16x32_bf16 v[18:21], v[204:207], v[228:231], 0
	v_mfma_f32_16x16x32_bf16 v[10:13], v[192:195], v[236:239], 0
	v_mfma_f32_16x16x32_bf16 v[2:5], v[204:207], v[236:239], 0
	v_mfma_f32_16x16x32_bf16 v[58:61], v[196:199], v[216:219], v[58:61]
	v_mfma_f32_16x16x32_bf16 v[50:53], v[208:211], v[216:219], v[50:53]
	v_mfma_f32_16x16x32_bf16 v[42:45], v[196:199], v[224:227], v[42:45]
	v_mfma_f32_16x16x32_bf16 v[34:37], v[208:211], v[224:227], v[34:37]
	v_mfma_f32_16x16x32_bf16 v[26:29], v[196:199], v[232:235], v[26:29]
	v_mfma_f32_16x16x32_bf16 v[18:21], v[208:211], v[232:235], v[18:21]
	v_mfma_f32_16x16x32_bf16 v[10:13], v[196:199], v[240:243], v[10:13]
	v_mfma_f32_16x16x32_bf16 v[2:5], v[208:211], v[240:243], v[2:5]
	s_barrier
	s_setprio 0
	s_add_i32 s29, 0, 0x18000
	v_add_u32_e32 v172, s29, v179
	s_add_i32 s37, 0, 0x1c000
	ds_read_b128 v[130:133], v172
	ds_read_b128 v[180:183], v172 offset:1024
	ds_read_b128 v[184:187], v172 offset:2048
	ds_read_b128 v[188:191], v172 offset:3072
	v_add_u32_e32 v172, s37, v179
	ds_read_b128 v[192:195], v172
	ds_read_b128 v[196:199], v172 offset:1024
	ds_read_b128 v[204:207], v172 offset:2048
	ds_read_b128 v[208:211], v172 offset:3072
	s_add_u32 s72, s72, 0x40000
	s_addc_u32 s73, s73, 0
	s_mov_b32 m0, s93
	ds_read_b128 v[212:215], v143 offset:32768
	ds_read_b128 v[216:219], v143 offset:33792
	ds_read_b128 v[220:223], v143 offset:34816
	ds_read_b128 v[224:227], v143 offset:35840
	ds_read_b128 v[228:231], v143 offset:36864
	ds_read_b128 v[232:235], v143 offset:37888
	ds_read_b128 v[236:239], v143 offset:38912
	ds_read_b128 v[240:243], v143 offset:39936
	global_load_lds_dwordx4 v140, s[72:73]
	s_mov_b32 m0, s33
	s_nop 0
	global_load_lds_dwordx4 v136, s[72:73]
	s_waitcnt vmcnt(8)
	s_waitcnt lgkmcnt(0)
	s_setprio 1
	s_barrier
	v_mfma_f32_16x16x32_bf16 v[126:129], v[130:133], v[212:215], v[126:129]
	v_mfma_f32_16x16x32_bf16 v[118:121], v[184:187], v[212:215], v[118:121]
	v_mfma_f32_16x16x32_bf16 v[110:113], v[130:133], v[220:223], v[110:113]
	v_mfma_f32_16x16x32_bf16 v[102:105], v[184:187], v[220:223], v[102:105]
	v_mfma_f32_16x16x32_bf16 v[94:97], v[130:133], v[228:231], v[94:97]
	v_mfma_f32_16x16x32_bf16 v[86:89], v[184:187], v[228:231], v[86:89]
	v_mfma_f32_16x16x32_bf16 v[78:81], v[130:133], v[236:239], v[78:81]
	v_mfma_f32_16x16x32_bf16 v[70:73], v[184:187], v[236:239], v[70:73]
	v_mfma_f32_16x16x32_bf16 v[126:129], v[180:183], v[216:219], v[126:129]
	v_mfma_f32_16x16x32_bf16 v[118:121], v[188:191], v[216:219], v[118:121]
	v_mfma_f32_16x16x32_bf16 v[110:113], v[180:183], v[224:227], v[110:113]
	v_mfma_f32_16x16x32_bf16 v[102:105], v[188:191], v[224:227], v[102:105]
	v_mfma_f32_16x16x32_bf16 v[94:97], v[180:183], v[232:235], v[94:97]
	v_mfma_f32_16x16x32_bf16 v[86:89], v[188:191], v[232:235], v[86:89]
	v_mfma_f32_16x16x32_bf16 v[78:81], v[180:183], v[240:243], v[78:81]
	v_mfma_f32_16x16x32_bf16 v[70:73], v[188:191], v[240:243], v[70:73]
	v_mfma_f32_16x16x32_bf16 v[122:125], v[192:195], v[212:215], v[122:125]
	v_mfma_f32_16x16x32_bf16 v[114:117], v[204:207], v[212:215], v[114:117]
	v_mfma_f32_16x16x32_bf16 v[106:109], v[192:195], v[220:223], v[106:109]
	v_mfma_f32_16x16x32_bf16 v[98:101], v[204:207], v[220:223], v[98:101]
	v_mfma_f32_16x16x32_bf16 v[90:93], v[192:195], v[228:231], v[90:93]
	v_mfma_f32_16x16x32_bf16 v[82:85], v[204:207], v[228:231], v[82:85]
	v_mfma_f32_16x16x32_bf16 v[74:77], v[192:195], v[236:239], v[74:77]
	v_mfma_f32_16x16x32_bf16 v[66:69], v[204:207], v[236:239], v[66:69]
	v_mfma_f32_16x16x32_bf16 v[122:125], v[196:199], v[216:219], v[122:125]
	v_mfma_f32_16x16x32_bf16 v[114:117], v[208:211], v[216:219], v[114:117]
	v_mfma_f32_16x16x32_bf16 v[106:109], v[196:199], v[224:227], v[106:109]
	v_mfma_f32_16x16x32_bf16 v[98:101], v[208:211], v[224:227], v[98:101]
	v_mfma_f32_16x16x32_bf16 v[90:93], v[196:199], v[232:235], v[90:93]
	v_mfma_f32_16x16x32_bf16 v[82:85], v[208:211], v[232:235], v[82:85]
	v_mfma_f32_16x16x32_bf16 v[74:77], v[196:199], v[240:243], v[74:77]
	v_mfma_f32_16x16x32_bf16 v[66:69], v[208:211], v[240:243], v[66:69]
	s_barrier
	s_setprio 0
	s_add_i32 s29, s29, s84
	v_lshl_add_u64 v[172:173], v[244:245], 0, s[24:25]
	s_mov_b32 m0, s29
	ds_read_b128 v[212:215], v143 offset:49152
	ds_read_b128 v[216:219], v143 offset:50176
	ds_read_b128 v[220:223], v143 offset:51200
	ds_read_b128 v[224:227], v143 offset:52224
	ds_read_b128 v[228:231], v143 offset:53248
	ds_read_b128 v[232:235], v143 offset:54272
	ds_read_b128 v[236:239], v143 offset:55296
	ds_read_b128 v[240:243], v143 offset:56320
	global_load_lds_dwordx4 v[172:173], off
	s_add_i32 m0, s29, 0x2000
	s_add_u32 s42, s42, 0x40080
	v_lshl_add_u64 v[172:173], v[246:247], 0, s[24:25]
	s_addc_u32 s43, s43, 0
	s_add_i32 s29, s37, s84
	global_load_lds_dwordx4 v[172:173], off
	s_mov_b32 m0, s29
	v_lshl_add_u64 v[170:171], v[170:171], 0, s[24:25]
	global_load_lds_dwordx4 v138, s[42:43]
	s_add_i32 m0, s29, 0x2000
	s_nop 0
	global_load_lds_dwordx4 v134, s[42:43]
	v_lshl_add_u64 v[172:173], v[248:249], 0, s[24:25]
	s_mov_b32 m0, s97
	s_nop 0
	global_load_lds_dwordx4 v[172:173], off
	s_mov_b32 m0, s3
	s_nop 0
	global_load_lds_dwordx4 v[170:171], off
	s_waitcnt vmcnt(8)
	s_waitcnt lgkmcnt(0)
	s_setprio 1
	s_barrier
	v_mfma_f32_16x16x32_bf16 v[62:65], v[130:133], v[212:215], v[62:65]
	v_mfma_f32_16x16x32_bf16 v[54:57], v[184:187], v[212:215], v[54:57]
	v_mfma_f32_16x16x32_bf16 v[46:49], v[130:133], v[220:223], v[46:49]
	v_mfma_f32_16x16x32_bf16 v[38:41], v[184:187], v[220:223], v[38:41]
	v_mfma_f32_16x16x32_bf16 v[30:33], v[130:133], v[228:231], v[30:33]
	v_mfma_f32_16x16x32_bf16 v[22:25], v[184:187], v[228:231], v[22:25]
	v_mfma_f32_16x16x32_bf16 v[14:17], v[130:133], v[236:239], v[14:17]
	v_mfma_f32_16x16x32_bf16 v[6:9], v[184:187], v[236:239], v[6:9]
	v_mfma_f32_16x16x32_bf16 v[62:65], v[180:183], v[216:219], v[62:65]
	v_mfma_f32_16x16x32_bf16 v[54:57], v[188:191], v[216:219], v[54:57]
	v_mfma_f32_16x16x32_bf16 v[46:49], v[180:183], v[224:227], v[46:49]
	v_mfma_f32_16x16x32_bf16 v[38:41], v[188:191], v[224:227], v[38:41]
	v_mfma_f32_16x16x32_bf16 v[30:33], v[180:183], v[232:235], v[30:33]
	v_mfma_f32_16x16x32_bf16 v[22:25], v[188:191], v[232:235], v[22:25]
	v_mfma_f32_16x16x32_bf16 v[14:17], v[180:183], v[240:243], v[14:17]
	v_mfma_f32_16x16x32_bf16 v[6:9], v[188:191], v[240:243], v[6:9]
	v_mfma_f32_16x16x32_bf16 v[58:61], v[192:195], v[212:215], v[58:61]
	v_mfma_f32_16x16x32_bf16 v[50:53], v[204:207], v[212:215], v[50:53]
	v_mfma_f32_16x16x32_bf16 v[42:45], v[192:195], v[220:223], v[42:45]
	v_mfma_f32_16x16x32_bf16 v[34:37], v[204:207], v[220:223], v[34:37]
	v_mfma_f32_16x16x32_bf16 v[26:29], v[192:195], v[228:231], v[26:29]
	v_mfma_f32_16x16x32_bf16 v[18:21], v[204:207], v[228:231], v[18:21]
	v_mfma_f32_16x16x32_bf16 v[10:13], v[192:195], v[236:239], v[10:13]
	v_mfma_f32_16x16x32_bf16 v[2:5], v[204:207], v[236:239], v[2:5]
	v_mfma_f32_16x16x32_bf16 v[58:61], v[196:199], v[216:219], v[58:61]
	v_mfma_f32_16x16x32_bf16 v[50:53], v[208:211], v[216:219], v[50:53]
	v_mfma_f32_16x16x32_bf16 v[42:45], v[196:199], v[224:227], v[42:45]
	v_mfma_f32_16x16x32_bf16 v[34:37], v[208:211], v[224:227], v[34:37]
	v_mfma_f32_16x16x32_bf16 v[26:29], v[196:199], v[232:235], v[26:29]
	v_mfma_f32_16x16x32_bf16 v[18:21], v[208:211], v[232:235], v[18:21]
	v_mfma_f32_16x16x32_bf16 v[10:13], v[196:199], v[240:243], v[10:13]
	v_mfma_f32_16x16x32_bf16 v[2:5], v[208:211], v[240:243], v[2:5]
	s_barrier
	s_setprio 0
	s_lshl_b32 s100, s84, 1
	v_lshl_add_u32 v204, v163, 5, s100
	v_add_u32_e32 v204, 0x20000, v204
	ds_read_b128 v[208:211], v204
	ds_read_b128 v[212:215], v204 offset:16
	s_waitcnt lgkmcnt(0)
	v_add_f32_e32 v208, v208, v209
	v_add_f32_e32 v210, v210, v211
	v_add_f32_e32 v212, v212, v213
	v_add_f32_e32 v214, v214, v215
	v_add_f32_e32 v208, v208, v210
	v_add_f32_e32 v212, v212, v214
	v_add_f32_e32 v208, v208, v212
	v_mov_b32_e32 v209, 0x358637bd
	s_nop 0
	v_add_f32_dpp v208, v208, v208 quad_perm:[1,0,3,2] row_mask:0xf bank_mask:0xf
	v_fmamk_f32 v208, v208, 0x3a800000, v209
	v_rsq_f32_e32 v209, v208
	s_nop 0
	v_mul_f32_e32 v209, 0xbfb8aa3b, v209
	ds_write_b64 v204, v[208:209]
	s_add_u32 s16, s16, 0x100
	s_addc_u32 s17, s17, 0
	s_add_u32 s56, s56, 0x100
	s_addc_u32 s57, s57, 0
	s_cmp_ge_i32 s86, s23
	s_mov_b32 s42, s86
	s_cbranch_scc0 .LBB7_357
	s_branch .Lpeelx_357

.Lswi_pref:
	v_lshlrev_b32_e32 v236, 6, v142
	v_add_u32_e32 v236, 0x20000, v236
	ds_read_b64 v[204:205], v236
	ds_read_b64 v[206:207], v236 offset:1024
	ds_read_b64 v[208:209], v236 offset:2048
	ds_read_b64 v[210:211], v236 offset:3072
	ds_read_b64 v[212:213], v236 offset:8192
	ds_read_b64 v[214:215], v236 offset:9216
	ds_read_b64 v[216:217], v236 offset:10240
	ds_read_b64 v[218:219], v236 offset:11264
	s_and_b64 vcc, exec, s[52:53]
	s_cbranch_vccz .LBB7_360

.LBB7_360:
	v_and_b32_e32 v131, 64, v163
	v_xor_b32_e32 v130, 16, v163
	v_add_u32_e32 v131, 64, v131
	v_cmp_lt_i32_e32 vcc, v130, v131
	v_lshl_add_u32 v132, s38, 8, v142
	v_ashrrev_i32_e32 v133, 31, v132
	v_xor_b32_e32 v130, 32, v163
	v_cmp_lt_i32_e32 vcc, v130, v131
	v_lshlrev_b64 v[130:131], 6, v[132:133]
	v_lshl_add_u64 v[130:131], v[144:145], 0, v[130:131]
	s_lshl_b32 s9, s10, 7
	s_mov_b32 s10, 0x358637bd
	v_mov_b64_e32 v[190:191], s[10:11]
	s_movk_i32 s10, 0x2000
	s_or_b32 s9, s9, s96
	s_ashr_i32 s16, s9, 6
	s_ashr_i32 s17, s16, 31
	s_mul_i32 s13, s38, 0x160000
	s_lshl_b64 s[16:17], s[16:17], 15
	s_add_u32 s9, s70, s13
	s_waitcnt lgkmcnt(0)
	v_pk_mul_f32 v[122:123], v[126:127], v[122:123]
	v_pk_mul_f32 v[114:115], v[118:119], v[114:115]
	v_pk_mul_f32 v[106:107], v[110:111], v[106:107]
	v_pk_mul_f32 v[98:99], v[102:103], v[98:99]
	v_add_co_u32_e32 v170, vcc, s10, v130
	s_mul_hi_i32 s10, s38, 0x160000
	s_nop 0
	v_addc_co_u32_e32 v171, vcc, 0, v131, vcc
	s_addc_u32 s10, s71, s10
	s_add_u32 s16, s9, s16
	s_addc_u32 s17, s10, s17
	v_pk_mul_f32 v[90:91], v[94:95], v[90:91]
	v_pk_mul_f32 v[82:83], v[86:87], v[82:83]
	v_pk_mul_f32 v[74:75], v[78:79], v[74:75]
	v_pk_mul_f32 v[66:67], v[70:71], v[66:67]
	v_pk_mul_f32 v[58:59], v[62:63], v[58:59]
	v_pk_mul_f32 v[50:51], v[54:55], v[50:51]
	v_pk_mul_f32 v[42:43], v[46:47], v[42:43]
	v_pk_mul_f32 v[34:35], v[38:39], v[34:35]
	v_pk_mul_f32 v[170:171], v[126:127], v[204:205] op_sel:[0,1] op_sel_hi:[1,1]
	v_mov_b64_e32 v[126:127], v[128:129]
	v_exp_f32_e32 v170, v170
	v_pk_mul_f32 v[128:129], v[126:127], v[204:205] op_sel:[0,1] op_sel_hi:[1,1]
	v_exp_f32_e32 v171, v171
	v_exp_f32_e32 v128, v128
	v_exp_f32_e32 v129, v129
	v_pk_mul_f32 v[124:125], v[126:127], v[124:125]
	v_pk_fma_f32 v[170:171], v[170:171], v[204:205], v[204:205] op_sel:[0,0,0] op_sel_hi:[1,0,0]
	v_pk_fma_f32 v[128:129], v[128:129], v[204:205], v[204:205] op_sel:[0,0,0] op_sel_hi:[1,0,0]
	v_rcp_f32_e32 v170, v170
	v_rcp_f32_e32 v171, v171
	v_rcp_f32_e32 v128, v128
	v_rcp_f32_e32 v129, v129
	v_pk_mul_f32 v[122:123], v[122:123], v[170:171]
	v_pk_mul_f32 v[124:125], v[124:125], v[128:129]
	v_cvt_pk_bf16_f32 v122, v122, v123
	v_cvt_pk_bf16_f32 v123, v124, v125
	v_pk_mul_f32 v[124:125], v[118:119], v[204:205] op_sel:[0,1] op_sel_hi:[1,1]
	s_nop 1
	v_exp_f32_e32 v124, v124
	v_exp_f32_e32 v125, v125
	s_nop 1
	v_pk_fma_f32 v[124:125], v[124:125], v[204:205], v[204:205] op_sel:[0,0,0] op_sel_hi:[1,0,0]
	s_nop 0
	v_rcp_f32_e32 v124, v124
	v_rcp_f32_e32 v125, v125
	s_nop 0
	v_pk_mul_f32 v[114:115], v[114:115], v[124:125]
	s_waitcnt lgkmcnt(0)
	v_cvt_pk_bf16_f32 v124, v114, v115
	v_mov_b64_e32 v[114:115], v[120:121]
	v_pk_mul_f32 v[118:119], v[114:115], v[204:205] op_sel:[0,1] op_sel_hi:[1,1]
	v_pk_mul_f32 v[114:115], v[114:115], v[116:117]
	v_exp_f32_e32 v118, v118
	v_exp_f32_e32 v119, v119
	s_nop 0
	v_pk_fma_f32 v[118:119], v[118:119], v[204:205], v[204:205] op_sel:[0,0,0] op_sel_hi:[1,0,0]
	v_rcp_f32_e32 v118, v118
	v_rcp_f32_e32 v119, v119
	s_nop 0
	v_pk_mul_f32 v[114:115], v[114:115], v[118:119]
	s_nop 0
	v_cvt_pk_bf16_f32 v125, v114, v115
	v_lshl_add_u64 v[114:115], s[16:17], 0, v[146:147]
	v_lshl_add_u64 v[114:115], v[114:115], 0, v[0:1]
	global_store_dwordx4 v[114:115], v[122:125], off nt
	v_pk_mul_f32 v[114:115], v[110:111], v[206:207] op_sel:[0,1] op_sel_hi:[1,1]
	v_mov_b64_e32 v[110:111], v[112:113]
	v_exp_f32_e32 v114, v114
	v_pk_mul_f32 v[112:113], v[110:111], v[206:207] op_sel:[0,1] op_sel_hi:[1,1]
	v_exp_f32_e32 v115, v115
	v_exp_f32_e32 v112, v112
	v_exp_f32_e32 v113, v113
	v_pk_mul_f32 v[108:109], v[110:111], v[108:109]
	v_pk_fma_f32 v[114:115], v[114:115], v[206:207], v[206:207] op_sel:[0,0,0] op_sel_hi:[1,0,0]
	v_pk_fma_f32 v[112:113], v[112:113], v[206:207], v[206:207] op_sel:[0,0,0] op_sel_hi:[1,0,0]
	v_rcp_f32_e32 v114, v114
	v_rcp_f32_e32 v115, v115
	v_rcp_f32_e32 v112, v112
	v_rcp_f32_e32 v113, v113
	v_pk_mul_f32 v[106:107], v[106:107], v[114:115]
	v_pk_mul_f32 v[108:109], v[108:109], v[112:113]
	v_cvt_pk_bf16_f32 v106, v106, v107
	v_cvt_pk_bf16_f32 v107, v108, v109
	v_pk_mul_f32 v[108:109], v[102:103], v[206:207] op_sel:[0,1] op_sel_hi:[1,1]
	v_exp_f32_e32 v108, v108
	v_exp_f32_e32 v109, v109
	v_pk_mul_f32 v[26:27], v[30:31], v[26:27]
	v_pk_fma_f32 v[108:109], v[108:109], v[206:207], v[206:207] op_sel:[0,0,0] op_sel_hi:[1,0,0]
	v_rcp_f32_e32 v108, v108
	v_rcp_f32_e32 v109, v109
	v_pk_mul_f32 v[18:19], v[22:23], v[18:19]
	v_pk_mul_f32 v[98:99], v[98:99], v[108:109]
	v_cvt_pk_bf16_f32 v108, v98, v99
	v_mov_b64_e32 v[98:99], v[104:105]
	v_pk_mul_f32 v[102:103], v[98:99], v[206:207] op_sel:[0,1] op_sel_hi:[1,1]
	v_pk_mul_f32 v[98:99], v[98:99], v[100:101]
	v_exp_f32_e32 v102, v102
	v_exp_f32_e32 v103, v103
	s_nop 0
	v_pk_fma_f32 v[102:103], v[102:103], v[206:207], v[206:207] op_sel:[0,0,0] op_sel_hi:[1,0,0]
	v_rcp_f32_e32 v102, v102
	v_rcp_f32_e32 v103, v103
	v_pk_mul_f32 v[10:11], v[14:15], v[10:11]
	v_pk_mul_f32 v[98:99], v[98:99], v[102:103]
	v_cvt_pk_bf16_f32 v109, v98, v99
	v_lshl_add_u64 v[98:99], s[16:17], 0, v[148:149]
	v_lshl_add_u64 v[98:99], v[98:99], 0, v[0:1]
	global_store_dwordx4 v[98:99], v[106:109], off nt
	v_pk_mul_f32 v[98:99], v[94:95], v[208:209] op_sel:[0,1] op_sel_hi:[1,1]
	v_mov_b64_e32 v[94:95], v[96:97]
	v_exp_f32_e32 v98, v98
	v_pk_mul_f32 v[96:97], v[94:95], v[208:209] op_sel:[0,1] op_sel_hi:[1,1]
	v_exp_f32_e32 v99, v99
	v_exp_f32_e32 v96, v96
	v_exp_f32_e32 v97, v97
	v_pk_mul_f32 v[92:93], v[94:95], v[92:93]
	v_pk_fma_f32 v[98:99], v[98:99], v[208:209], v[208:209] op_sel:[0,0,0] op_sel_hi:[1,0,0]
	v_pk_fma_f32 v[96:97], v[96:97], v[208:209], v[208:209] op_sel:[0,0,0] op_sel_hi:[1,0,0]
	v_rcp_f32_e32 v98, v98
	v_rcp_f32_e32 v99, v99
	v_rcp_f32_e32 v96, v96
	v_rcp_f32_e32 v97, v97
	v_pk_mul_f32 v[2:3], v[6:7], v[2:3]
	v_pk_mul_f32 v[90:91], v[90:91], v[98:99]
	v_pk_mul_f32 v[92:93], v[92:93], v[96:97]
	v_cvt_pk_bf16_f32 v90, v90, v91
	s_andn2_b64 vcc, exec, s[40:41]
	v_cvt_pk_bf16_f32 v91, v92, v93
	v_pk_mul_f32 v[92:93], v[86:87], v[208:209] op_sel:[0,1] op_sel_hi:[1,1]
	s_nop 0
	v_exp_f32_e32 v92, v92
	v_exp_f32_e32 v93, v93
	s_nop 0
	v_pk_fma_f32 v[92:93], v[92:93], v[208:209], v[208:209] op_sel:[0,0,0] op_sel_hi:[1,0,0]
	s_nop 0
	v_rcp_f32_e32 v92, v92
	v_rcp_f32_e32 v93, v93
	s_nop 0
	v_pk_mul_f32 v[82:83], v[82:83], v[92:93]
	s_nop 0
	v_cvt_pk_bf16_f32 v92, v82, v83
	v_mov_b64_e32 v[82:83], v[88:89]
	s_nop 0
	v_pk_mul_f32 v[86:87], v[82:83], v[208:209] op_sel:[0,1] op_sel_hi:[1,1]
	v_pk_mul_f32 v[82:83], v[82:83], v[84:85]
	v_exp_f32_e32 v86, v86
	v_exp_f32_e32 v87, v87
	s_nop 0
	v_pk_fma_f32 v[86:87], v[86:87], v[208:209], v[208:209] op_sel:[0,0,0] op_sel_hi:[1,0,0]
	s_nop 0
	v_rcp_f32_e32 v86, v86
	v_rcp_f32_e32 v87, v87
	s_nop 0
	v_pk_mul_f32 v[82:83], v[82:83], v[86:87]
	s_nop 0
	v_cvt_pk_bf16_f32 v93, v82, v83
	v_lshl_add_u64 v[82:83], s[16:17], 0, v[150:151]
	v_lshl_add_u64 v[82:83], v[82:83], 0, v[0:1]
	global_store_dwordx4 v[82:83], v[90:93], off nt
	v_pk_mul_f32 v[82:83], v[78:79], v[210:211] op_sel:[0,1] op_sel_hi:[1,1]
	v_mov_b64_e32 v[78:79], v[80:81]
	v_exp_f32_e32 v82, v82
	v_pk_mul_f32 v[80:81], v[78:79], v[210:211] op_sel:[0,1] op_sel_hi:[1,1]
	v_exp_f32_e32 v83, v83
	v_exp_f32_e32 v80, v80
	v_exp_f32_e32 v81, v81
	v_pk_mul_f32 v[76:77], v[78:79], v[76:77]
	v_pk_fma_f32 v[82:83], v[82:83], v[210:211], v[210:211] op_sel:[0,0,0] op_sel_hi:[1,0,0]
	v_pk_fma_f32 v[80:81], v[80:81], v[210:211], v[210:211] op_sel:[0,0,0] op_sel_hi:[1,0,0]
	v_rcp_f32_e32 v82, v82
	v_rcp_f32_e32 v83, v83
	v_rcp_f32_e32 v80, v80
	v_rcp_f32_e32 v81, v81
	v_pk_mul_f32 v[74:75], v[74:75], v[82:83]
	s_nop 0
	v_cvt_pk_bf16_f32 v74, v74, v75
	v_pk_mul_f32 v[76:77], v[76:77], v[80:81]
	s_nop 0
	v_cvt_pk_bf16_f32 v75, v76, v77
	v_pk_mul_f32 v[76:77], v[70:71], v[210:211] op_sel:[0,1] op_sel_hi:[1,1]
	s_nop 0
	v_exp_f32_e32 v76, v76
	v_exp_f32_e32 v77, v77
	s_nop 0
	v_pk_fma_f32 v[76:77], v[76:77], v[210:211], v[210:211] op_sel:[0,0,0] op_sel_hi:[1,0,0]
	s_nop 0
	v_rcp_f32_e32 v76, v76
	v_rcp_f32_e32 v77, v77
	s_nop 0
	v_pk_mul_f32 v[66:67], v[66:67], v[76:77]
	s_nop 0
	v_cvt_pk_bf16_f32 v76, v66, v67
	v_mov_b64_e32 v[66:67], v[72:73]
	s_nop 0
	v_pk_mul_f32 v[70:71], v[66:67], v[210:211] op_sel:[0,1] op_sel_hi:[1,1]
	v_pk_mul_f32 v[66:67], v[66:67], v[68:69]
	v_exp_f32_e32 v70, v70
	v_exp_f32_e32 v71, v71
	s_nop 0
	v_pk_fma_f32 v[70:71], v[70:71], v[210:211], v[210:211] op_sel:[0,0,0] op_sel_hi:[1,0,0]
	s_nop 0
	v_rcp_f32_e32 v70, v70
	v_rcp_f32_e32 v71, v71
	s_nop 0
	v_pk_mul_f32 v[66:67], v[66:67], v[70:71]
	s_nop 0
	v_cvt_pk_bf16_f32 v77, v66, v67
	v_lshl_add_u64 v[66:67], s[16:17], 0, v[152:153]
	v_lshl_add_u64 v[66:67], v[66:67], 0, v[0:1]
	global_store_dwordx4 v[66:67], v[74:77], off nt
	v_pk_mul_f32 v[66:67], v[62:63], v[212:213] op_sel:[0,1] op_sel_hi:[1,1]
	v_mov_b64_e32 v[62:63], v[64:65]
	v_exp_f32_e32 v66, v66
	v_pk_mul_f32 v[64:65], v[62:63], v[212:213] op_sel:[0,1] op_sel_hi:[1,1]
	v_exp_f32_e32 v67, v67
	v_exp_f32_e32 v64, v64
	v_exp_f32_e32 v65, v65
	v_pk_mul_f32 v[60:61], v[62:63], v[60:61]
	v_pk_fma_f32 v[66:67], v[66:67], v[212:213], v[212:213] op_sel:[0,0,0] op_sel_hi:[1,0,0]
	v_pk_fma_f32 v[64:65], v[64:65], v[212:213], v[212:213] op_sel:[0,0,0] op_sel_hi:[1,0,0]
	v_rcp_f32_e32 v66, v66
	v_rcp_f32_e32 v67, v67
	v_rcp_f32_e32 v64, v64
	v_rcp_f32_e32 v65, v65
	v_pk_mul_f32 v[58:59], v[58:59], v[66:67]
	s_nop 0
	v_cvt_pk_bf16_f32 v58, v58, v59
	v_pk_mul_f32 v[60:61], v[60:61], v[64:65]
	s_nop 0
	v_cvt_pk_bf16_f32 v59, v60, v61
	v_pk_mul_f32 v[60:61], v[54:55], v[212:213] op_sel:[0,1] op_sel_hi:[1,1]
	s_nop 0
	v_exp_f32_e32 v60, v60
	v_exp_f32_e32 v61, v61
	s_nop 0
	v_pk_fma_f32 v[60:61], v[60:61], v[212:213], v[212:213] op_sel:[0,0,0] op_sel_hi:[1,0,0]
	s_nop 0
	v_rcp_f32_e32 v60, v60
	v_rcp_f32_e32 v61, v61
	s_nop 0
	v_pk_mul_f32 v[50:51], v[50:51], v[60:61]
	s_nop 0
	v_cvt_pk_bf16_f32 v60, v50, v51
	v_mov_b64_e32 v[50:51], v[56:57]
	s_nop 0
	v_pk_mul_f32 v[54:55], v[50:51], v[212:213] op_sel:[0,1] op_sel_hi:[1,1]
	v_pk_mul_f32 v[50:51], v[50:51], v[52:53]
	v_exp_f32_e32 v54, v54
	v_exp_f32_e32 v55, v55
	s_nop 0
	v_pk_fma_f32 v[54:55], v[54:55], v[212:213], v[212:213] op_sel:[0,0,0] op_sel_hi:[1,0,0]
	s_nop 0
	v_rcp_f32_e32 v54, v54
	v_rcp_f32_e32 v55, v55
	s_nop 0
	v_pk_mul_f32 v[50:51], v[50:51], v[54:55]
	s_nop 0
	v_cvt_pk_bf16_f32 v61, v50, v51
	v_lshl_add_u64 v[50:51], s[16:17], 0, v[154:155]
	v_lshl_add_u64 v[50:51], v[50:51], 0, v[0:1]
	global_store_dwordx4 v[50:51], v[58:61], off nt
	v_pk_mul_f32 v[50:51], v[46:47], v[214:215] op_sel:[0,1] op_sel_hi:[1,1]
	v_mov_b64_e32 v[46:47], v[48:49]
	v_exp_f32_e32 v50, v50
	v_pk_mul_f32 v[48:49], v[46:47], v[214:215] op_sel:[0,1] op_sel_hi:[1,1]
	v_exp_f32_e32 v51, v51
	v_exp_f32_e32 v48, v48
	v_exp_f32_e32 v49, v49
	v_pk_mul_f32 v[44:45], v[46:47], v[44:45]
	v_pk_fma_f32 v[50:51], v[50:51], v[214:215], v[214:215] op_sel:[0,0,0] op_sel_hi:[1,0,0]
	v_pk_fma_f32 v[48:49], v[48:49], v[214:215], v[214:215] op_sel:[0,0,0] op_sel_hi:[1,0,0]
	v_rcp_f32_e32 v50, v50
	v_rcp_f32_e32 v51, v51
	v_rcp_f32_e32 v48, v48
	v_rcp_f32_e32 v49, v49
	v_pk_mul_f32 v[42:43], v[42:43], v[50:51]
	s_nop 0
	v_cvt_pk_bf16_f32 v42, v42, v43
	v_pk_mul_f32 v[44:45], v[44:45], v[48:49]
	s_nop 0
	v_cvt_pk_bf16_f32 v43, v44, v45
	v_pk_mul_f32 v[44:45], v[38:39], v[214:215] op_sel:[0,1] op_sel_hi:[1,1]
	s_nop 0
	v_exp_f32_e32 v44, v44
	v_exp_f32_e32 v45, v45
	s_nop 0
	v_pk_fma_f32 v[44:45], v[44:45], v[214:215], v[214:215] op_sel:[0,0,0] op_sel_hi:[1,0,0]
	s_nop 0
	v_rcp_f32_e32 v44, v44
	v_rcp_f32_e32 v45, v45
	s_nop 0
	v_pk_mul_f32 v[34:35], v[34:35], v[44:45]
	s_nop 0
	v_cvt_pk_bf16_f32 v44, v34, v35
	v_mov_b64_e32 v[34:35], v[40:41]
	s_nop 0
	v_pk_mul_f32 v[38:39], v[34:35], v[214:215] op_sel:[0,1] op_sel_hi:[1,1]
	v_pk_mul_f32 v[34:35], v[34:35], v[36:37]
	v_exp_f32_e32 v38, v38
	v_exp_f32_e32 v39, v39
	s_nop 0
	v_pk_fma_f32 v[38:39], v[38:39], v[214:215], v[214:215] op_sel:[0,0,0] op_sel_hi:[1,0,0]
	s_nop 0
	v_rcp_f32_e32 v38, v38
	v_rcp_f32_e32 v39, v39
	s_nop 0
	v_pk_mul_f32 v[34:35], v[34:35], v[38:39]
	s_nop 0
	v_cvt_pk_bf16_f32 v45, v34, v35
	v_lshl_add_u64 v[34:35], s[16:17], 0, v[156:157]
	v_lshl_add_u64 v[34:35], v[34:35], 0, v[0:1]
	global_store_dwordx4 v[34:35], v[42:45], off nt
	v_pk_mul_f32 v[34:35], v[30:31], v[216:217] op_sel:[0,1] op_sel_hi:[1,1]
	v_mov_b64_e32 v[30:31], v[32:33]
	v_exp_f32_e32 v34, v34
	v_pk_mul_f32 v[32:33], v[30:31], v[216:217] op_sel:[0,1] op_sel_hi:[1,1]
	v_exp_f32_e32 v35, v35
	v_exp_f32_e32 v32, v32
	v_exp_f32_e32 v33, v33
	v_pk_mul_f32 v[28:29], v[30:31], v[28:29]
	v_pk_fma_f32 v[34:35], v[34:35], v[216:217], v[216:217] op_sel:[0,0,0] op_sel_hi:[1,0,0]
	v_pk_fma_f32 v[32:33], v[32:33], v[216:217], v[216:217] op_sel:[0,0,0] op_sel_hi:[1,0,0]
	v_rcp_f32_e32 v34, v34
	v_rcp_f32_e32 v35, v35
	v_rcp_f32_e32 v32, v32
	v_rcp_f32_e32 v33, v33
	v_pk_mul_f32 v[26:27], v[26:27], v[34:35]
	s_nop 0
	v_cvt_pk_bf16_f32 v26, v26, v27
	v_pk_mul_f32 v[28:29], v[28:29], v[32:33]
	s_nop 0
	v_cvt_pk_bf16_f32 v27, v28, v29
	v_pk_mul_f32 v[28:29], v[22:23], v[216:217] op_sel:[0,1] op_sel_hi:[1,1]
	s_nop 0
	v_exp_f32_e32 v28, v28
	v_exp_f32_e32 v29, v29
	s_nop 0
	v_pk_fma_f32 v[28:29], v[28:29], v[216:217], v[216:217] op_sel:[0,0,0] op_sel_hi:[1,0,0]
	s_nop 0
	v_rcp_f32_e32 v28, v28
	v_rcp_f32_e32 v29, v29
	s_nop 0
	v_pk_mul_f32 v[18:19], v[18:19], v[28:29]
	s_nop 0
	v_cvt_pk_bf16_f32 v28, v18, v19
	v_mov_b64_e32 v[18:19], v[24:25]
	s_nop 0
	v_pk_mul_f32 v[22:23], v[18:19], v[216:217] op_sel:[0,1] op_sel_hi:[1,1]
	v_pk_mul_f32 v[18:19], v[18:19], v[20:21]
	v_exp_f32_e32 v22, v22
	v_exp_f32_e32 v23, v23
	s_nop 0
	v_pk_fma_f32 v[22:23], v[22:23], v[216:217], v[216:217] op_sel:[0,0,0] op_sel_hi:[1,0,0]
	s_nop 0
	v_rcp_f32_e32 v22, v22
	v_rcp_f32_e32 v23, v23
	s_nop 0
	v_pk_mul_f32 v[18:19], v[18:19], v[22:23]
	s_nop 0
	v_cvt_pk_bf16_f32 v29, v18, v19
	v_lshl_add_u64 v[18:19], s[16:17], 0, v[158:159]
	v_lshl_add_u64 v[18:19], v[18:19], 0, v[0:1]
	global_store_dwordx4 v[18:19], v[26:29], off nt
	v_pk_mul_f32 v[18:19], v[14:15], v[218:219] op_sel:[0,1] op_sel_hi:[1,1]
	v_mov_b64_e32 v[14:15], v[16:17]
	v_exp_f32_e32 v18, v18
	v_pk_mul_f32 v[16:17], v[14:15], v[218:219] op_sel:[0,1] op_sel_hi:[1,1]
	v_exp_f32_e32 v19, v19
	v_exp_f32_e32 v16, v16
	v_exp_f32_e32 v17, v17
	v_pk_mul_f32 v[12:13], v[14:15], v[12:13]
	v_pk_fma_f32 v[18:19], v[18:19], v[218:219], v[218:219] op_sel:[0,0,0] op_sel_hi:[1,0,0]
	v_pk_fma_f32 v[16:17], v[16:17], v[218:219], v[218:219] op_sel:[0,0,0] op_sel_hi:[1,0,0]
	v_rcp_f32_e32 v18, v18
	v_rcp_f32_e32 v19, v19
	v_rcp_f32_e32 v16, v16
	v_rcp_f32_e32 v17, v17
	v_pk_mul_f32 v[10:11], v[10:11], v[18:19]
	s_nop 0
	v_cvt_pk_bf16_f32 v10, v10, v11
	v_pk_mul_f32 v[12:13], v[12:13], v[16:17]
	s_nop 0
	v_cvt_pk_bf16_f32 v11, v12, v13
	v_pk_mul_f32 v[12:13], v[6:7], v[218:219] op_sel:[0,1] op_sel_hi:[1,1]
	s_nop 0
	v_exp_f32_e32 v12, v12
	v_exp_f32_e32 v13, v13
	s_nop 0
	v_pk_fma_f32 v[12:13], v[12:13], v[218:219], v[218:219] op_sel:[0,0,0] op_sel_hi:[1,0,0]
	s_nop 0
	v_rcp_f32_e32 v12, v12
	v_rcp_f32_e32 v13, v13
	s_nop 0
	v_pk_mul_f32 v[2:3], v[2:3], v[12:13]
	s_nop 0
	v_cvt_pk_bf16_f32 v12, v2, v3
	v_mov_b64_e32 v[2:3], v[8:9]
	s_nop 0
	v_pk_mul_f32 v[6:7], v[2:3], v[218:219] op_sel:[0,1] op_sel_hi:[1,1]
	v_pk_mul_f32 v[2:3], v[2:3], v[4:5]
	v_exp_f32_e32 v6, v6
	v_exp_f32_e32 v7, v7
	s_nop 0
	v_pk_fma_f32 v[6:7], v[6:7], v[218:219], v[218:219] op_sel:[0,0,0] op_sel_hi:[1,0,0]
	s_nop 0
	v_rcp_f32_e32 v6, v6
	v_rcp_f32_e32 v7, v7
	s_nop 0
	v_pk_mul_f32 v[2:3], v[2:3], v[6:7]
	s_nop 0
	v_cvt_pk_bf16_f32 v13, v2, v3
	v_lshl_add_u64 v[2:3], s[16:17], 0, v[160:161]
	v_lshl_add_u64 v[2:3], v[2:3], 0, v[0:1]
	global_store_dwordx4 v[2:3], v[10:13], off nt
	s_mov_b64 s[16:17], -1
	s_cbranch_vccnz .LBB7_352
	s_andn2_b64 vcc, exec, s[50:51]
	s_cbranch_vccnz .LBB7_351
	s_branch .LBB7_351
